# code placement: both GEMM K-loop heads on 64-byte boundaries
# speedup vs baseline: 1.0020x; 1.0020x over previous
.LBB0_366:
	s_ashr_i32 s25, s24, 31
	s_lshl_b64 s[26:27], s[24:25], 19
	s_add_u32 s26, s42, s26
	s_addc_u32 s27, s43, s27
	s_and_b64 s[28:29], s[4:5], exec
	s_cselect_b32 s1, s27, s35
	s_cselect_b32 s25, s26, s34
	s_ashr_i32 s23, s22, 31
	s_lshl_b64 s[28:29], s[22:23], 19
	s_add_u32 s28, s44, s28
	s_addc_u32 s29, s45, s29
	s_and_b64 s[38:39], s[4:5], exec
	s_cselect_b32 s23, s29, s37
	s_cselect_b32 s31, s28, s36
	s_add_u32 s34, s34, 0x40080
	s_addc_u32 s35, s35, 0
	s_add_u32 s40, s36, 0x100
	v_mov_b32_e32 v2, 0
	s_addc_u32 s41, s37, 0
	s_mov_b32 s65, -2
	v_mov_b32_e32 v3, v2
	v_mov_b32_e32 v4, v2
	v_mov_b32_e32 v5, v2
	v_mov_b32_e32 v6, v2
	v_mov_b32_e32 v7, v2
	v_mov_b32_e32 v8, v2
	v_mov_b32_e32 v9, v2
	v_mov_b32_e32 v18, v2
	v_mov_b32_e32 v19, v2
	v_mov_b32_e32 v20, v2
	v_mov_b32_e32 v21, v2
	v_mov_b32_e32 v22, v2
	v_mov_b32_e32 v23, v2
	v_mov_b32_e32 v24, v2
	v_mov_b32_e32 v25, v2
	s_waitcnt vmcnt(0)
	v_mov_b32_e32 v34, v2
	v_mov_b32_e32 v35, v2
	v_mov_b32_e32 v36, v2
	v_mov_b32_e32 v37, v2
	v_mov_b32_e32 v38, v2
	v_mov_b32_e32 v39, v2
	v_mov_b32_e32 v40, v2
	v_mov_b32_e32 v41, v2
	v_mov_b32_e32 v50, v2
	v_mov_b32_e32 v51, v2
	v_mov_b32_e32 v52, v2
	v_mov_b32_e32 v53, v2
	v_mov_b32_e32 v54, v2
	v_mov_b32_e32 v55, v2
	v_mov_b32_e32 v56, v2
	v_mov_b32_e32 v57, v2
	v_mov_b32_e32 v10, v2
	v_mov_b32_e32 v11, v2
	v_mov_b32_e32 v12, v2
	v_mov_b32_e32 v13, v2
	v_mov_b32_e32 v14, v2
	v_mov_b32_e32 v15, v2
	v_mov_b32_e32 v16, v2
	v_mov_b32_e32 v17, v2
	v_mov_b32_e32 v26, v2
	v_mov_b32_e32 v27, v2
	v_mov_b32_e32 v28, v2
	v_mov_b32_e32 v29, v2
	v_mov_b32_e32 v30, v2
	v_mov_b32_e32 v31, v2
	v_mov_b32_e32 v32, v2
	v_mov_b32_e32 v33, v2
	v_mov_b32_e32 v42, v2
	v_mov_b32_e32 v43, v2
	v_mov_b32_e32 v44, v2
	v_mov_b32_e32 v45, v2
	v_mov_b32_e32 v46, v2
	v_mov_b32_e32 v47, v2
	v_mov_b32_e32 v48, v2
	v_mov_b32_e32 v49, v2
	v_mov_b32_e32 v58, v2
	v_mov_b32_e32 v59, v2
	v_mov_b32_e32 v60, v2
	v_mov_b32_e32 v61, v2
	v_mov_b32_e32 v62, v2
	v_mov_b32_e32 v63, v2
	v_mov_b32_e32 v64, v2
	v_mov_b32_e32 v65, v2
	v_mov_b32_e32 v66, v2
	v_mov_b32_e32 v67, v2
	v_mov_b32_e32 v68, v2
	v_mov_b32_e32 v69, v2
	v_mov_b32_e32 v70, v2
	v_mov_b32_e32 v71, v2
	v_mov_b32_e32 v72, v2
	v_mov_b32_e32 v73, v2
	v_mov_b32_e32 v82, v2
	v_mov_b32_e32 v83, v2
	v_mov_b32_e32 v84, v2
	v_mov_b32_e32 v85, v2
	v_mov_b32_e32 v86, v2
	v_mov_b32_e32 v87, v2
	v_mov_b32_e32 v88, v2
	v_mov_b32_e32 v89, v2
	v_mov_b32_e32 v98, v2
	v_mov_b32_e32 v99, v2
	v_mov_b32_e32 v100, v2
	v_mov_b32_e32 v101, v2
	v_mov_b32_e32 v102, v2
	v_mov_b32_e32 v103, v2
	v_mov_b32_e32 v104, v2
	v_mov_b32_e32 v105, v2
	v_mov_b32_e32 v114, v2
	v_mov_b32_e32 v115, v2
	v_mov_b32_e32 v116, v2
	v_mov_b32_e32 v117, v2
	v_mov_b32_e32 v118, v2
	v_mov_b32_e32 v119, v2
	v_mov_b32_e32 v120, v2
	v_mov_b32_e32 v121, v2
	v_mov_b32_e32 v74, v2
	v_mov_b32_e32 v75, v2
	v_mov_b32_e32 v76, v2
	v_mov_b32_e32 v77, v2
	v_mov_b32_e32 v78, v2
	v_mov_b32_e32 v79, v2
	v_mov_b32_e32 v80, v2
	v_mov_b32_e32 v81, v2
	v_mov_b32_e32 v90, v2
	v_mov_b32_e32 v91, v2
	v_mov_b32_e32 v92, v2
	v_mov_b32_e32 v93, v2
	v_mov_b32_e32 v94, v2
	v_mov_b32_e32 v95, v2
	v_mov_b32_e32 v96, v2
	v_mov_b32_e32 v97, v2
	v_mov_b32_e32 v106, v2
	v_mov_b32_e32 v107, v2
	v_mov_b32_e32 v108, v2
	v_mov_b32_e32 v109, v2
	v_mov_b32_e32 v110, v2
	v_mov_b32_e32 v111, v2
	v_mov_b32_e32 v112, v2
	v_mov_b32_e32 v113, v2
	v_mov_b32_e32 v122, v2
	v_mov_b32_e32 v123, v2
	v_mov_b32_e32 v124, v2
	v_mov_b32_e32 v125, v2
	v_mov_b32_e32 v126, v2
	v_mov_b32_e32 v127, v2
	v_mov_b32_e32 v128, v2
	v_mov_b32_e32 v129, v2
	.p2align	6

.LBB0_765:
	s_ashr_i32 s27, s26, 31
	s_lshl_b64 s[28:29], s[26:27], 19
	s_add_u32 s28, s42, s28
	s_addc_u32 s29, s43, s29
	s_and_b64 s[30:31], s[0:1], exec
	s_cselect_b32 s27, s29, s37
	s_cselect_b32 s59, s28, s36
	s_ashr_i32 s25, s24, 31
	s_lshl_b64 s[30:31], s[24:25], 19
	s_add_u32 s30, s44, s30
	s_addc_u32 s31, s45, s31
	s_and_b64 s[40:41], s[0:1], exec
	s_cselect_b32 s25, s31, s39
	s_cselect_b32 s60, s30, s38
	s_add_u32 s36, s36, 0x40080
	s_addc_u32 s37, s37, 0
	s_add_u32 s61, s38, 0x100
	v_mov_b32_e32 v0, 0
	s_addc_u32 s62, s39, 0
	s_mov_b32 s63, -2
	v_mov_b32_e32 v1, v0
	v_mov_b32_e32 v2, v0
	v_mov_b32_e32 v3, v0
	v_mov_b32_e32 v4, v0
	v_mov_b32_e32 v5, v0
	v_mov_b32_e32 v6, v0
	v_mov_b32_e32 v7, v0
	v_mov_b32_e32 v8, v0
	v_mov_b32_e32 v9, v0
	v_mov_b32_e32 v10, v0
	v_mov_b32_e32 v11, v0
	v_mov_b32_e32 v16, v0
	v_mov_b32_e32 v17, v0
	v_mov_b32_e32 v18, v0
	v_mov_b32_e32 v19, v0
	v_mov_b32_e32 v24, v0
	v_mov_b32_e32 v25, v0
	v_mov_b32_e32 v26, v0
	v_mov_b32_e32 v27, v0
	s_waitcnt vmcnt(0)
	v_mov_b32_e32 v32, v0
	v_mov_b32_e32 v33, v0
	v_mov_b32_e32 v34, v0
	v_mov_b32_e32 v35, v0
	v_mov_b32_e32 v40, v0
	v_mov_b32_e32 v41, v0
	v_mov_b32_e32 v42, v0
	v_mov_b32_e32 v43, v0
	v_mov_b32_e32 v48, v0
	v_mov_b32_e32 v49, v0
	v_mov_b32_e32 v50, v0
	v_mov_b32_e32 v51, v0
	v_mov_b32_e32 v12, v0
	v_mov_b32_e32 v13, v0
	v_mov_b32_e32 v14, v0
	v_mov_b32_e32 v15, v0
	v_mov_b32_e32 v20, v0
	v_mov_b32_e32 v21, v0
	v_mov_b32_e32 v22, v0
	v_mov_b32_e32 v23, v0
	v_mov_b32_e32 v28, v0
	v_mov_b32_e32 v29, v0
	v_mov_b32_e32 v30, v0
	v_mov_b32_e32 v31, v0
	v_mov_b32_e32 v36, v0
	v_mov_b32_e32 v37, v0
	v_mov_b32_e32 v38, v0
	v_mov_b32_e32 v39, v0
	v_mov_b32_e32 v44, v0
	v_mov_b32_e32 v45, v0
	v_mov_b32_e32 v46, v0
	v_mov_b32_e32 v47, v0
	v_mov_b32_e32 v52, v0
	v_mov_b32_e32 v53, v0
	v_mov_b32_e32 v54, v0
	v_mov_b32_e32 v55, v0
	v_mov_b32_e32 v56, v0
	v_mov_b32_e32 v57, v0
	v_mov_b32_e32 v58, v0
	v_mov_b32_e32 v59, v0
	v_mov_b32_e32 v60, v0
	v_mov_b32_e32 v61, v0
	v_mov_b32_e32 v62, v0
	v_mov_b32_e32 v63, v0
	v_mov_b32_e32 v64, v0
	v_mov_b32_e32 v65, v0
	v_mov_b32_e32 v66, v0
	v_mov_b32_e32 v67, v0
	v_mov_b32_e32 v68, v0
	v_mov_b32_e32 v69, v0
	v_mov_b32_e32 v70, v0
	v_mov_b32_e32 v71, v0
	v_mov_b32_e32 v72, v0
	v_mov_b32_e32 v73, v0
	v_mov_b32_e32 v74, v0
	v_mov_b32_e32 v75, v0
	v_mov_b32_e32 v80, v0
	v_mov_b32_e32 v81, v0
	v_mov_b32_e32 v82, v0
	v_mov_b32_e32 v83, v0
	v_mov_b32_e32 v92, v0
	v_mov_b32_e32 v93, v0
	v_mov_b32_e32 v94, v0
	v_mov_b32_e32 v95, v0
	v_mov_b32_e32 v100, v0
	v_mov_b32_e32 v101, v0
	v_mov_b32_e32 v102, v0
	v_mov_b32_e32 v103, v0
	v_mov_b32_e32 v104, v0
	v_mov_b32_e32 v105, v0
	v_mov_b32_e32 v106, v0
	v_mov_b32_e32 v107, v0
	v_mov_b32_e32 v112, v0
	v_mov_b32_e32 v113, v0
	v_mov_b32_e32 v114, v0
	v_mov_b32_e32 v115, v0
	v_mov_b32_e32 v76, v0
	v_mov_b32_e32 v77, v0
	v_mov_b32_e32 v78, v0
	v_mov_b32_e32 v79, v0
	v_mov_b32_e32 v84, v0
	v_mov_b32_e32 v85, v0
	v_mov_b32_e32 v86, v0
	v_mov_b32_e32 v87, v0
	v_mov_b32_e32 v88, v0
	v_mov_b32_e32 v89, v0
	v_mov_b32_e32 v90, v0
	v_mov_b32_e32 v91, v0
	v_mov_b32_e32 v96, v0
	v_mov_b32_e32 v97, v0
	v_mov_b32_e32 v98, v0
	v_mov_b32_e32 v99, v0
	v_mov_b32_e32 v108, v0
	v_mov_b32_e32 v109, v0
	v_mov_b32_e32 v110, v0
	v_mov_b32_e32 v111, v0
	v_mov_b32_e32 v116, v0
	v_mov_b32_e32 v117, v0
	v_mov_b32_e32 v118, v0
	v_mov_b32_e32 v119, v0
	v_mov_b32_e32 v120, v0
	v_mov_b32_e32 v121, v0
	v_mov_b32_e32 v122, v0
	v_mov_b32_e32 v123, v0
	v_mov_b32_e32 v124, v0
	v_mov_b32_e32 v125, v0
	v_mov_b32_e32 v126, v0
	v_mov_b32_e32 v127, v0
	.p2align	6
